# A1 first-half stream: loop back edge rotated (barrier is the loop head; counter, exit test and loop-carried move sit before it; exit path has its own barrier copy)
# baseline (speedup 1.0000x reference)
; DI void rope_sc(float pos, int j, float& sn, float& cs) {
;   const float fr = exp2f(-(float)j * (LOG2_THETA / 32.f));
;   float tr = pos * fr * INV_2PI;
;   tr -= floorf(tr);
;   sn = __builtin_amdgcn_sinf(tr);
;   cs = __builtin_amdgcn_cosf(tr);
; }
; template <int NHQ, int NHKV>
; DI void attn_phase_l1(const u16* __restrict__ Q, const u16* __restrict__ K, const u16* __restrict__ Vt, u16* __restrict__ O, const float* __restrict__ qg, char* smem, const int wv) {
;     ...
;   for (int item = (G_ % 8 == 0) ? (b_ % 8) * (G_ / 8) + b_ / 8 : b_; item < NF; item += G_) {
;     const int hq = (item >> 4) % NHQ, sq = item / (16 * NHQ), q0 = NMETA + 256 * (item & 15);
;     const u16* Kb = K + (size_t)(sq * L) * LDK + (hq / (NHQ / NHKV)) * DQK;
;     const u16* Vb = Vt + (size_t)((sq * NHKV + hq / (NHQ / NHKV)) * 128) * LP;
;     const int pq = q0 + wave * 32 + r32;
;     {
;       const u16* qrow = Q + (size_t)(sq * L + pq) * 1280 + hq * DQK + hh * 8;
;       int hho = hh; asm volatile("" : "+v"(hho));
;       float ssq = 0.f;
; #pragma unroll
;       for (int i = 0; i < NS; ++i) {
;         qf[i] = *(const bf16x8*)(qrow + 16 * i);
;         float t8[8]; unpack8(__builtin_bit_cast(u32x4, qf[i]), t8);
; #pragma unroll
;         for (int e = 0; e < 8; ++e) ssq += t8[e] * t8[e];
;       }
;       ssq = xhalf_sum(ssq);
;       const float rn = rsqrtf(ssq * (1.f / DQK) + EPS) * (0.08838834764831845f * 1.4426950408889634f);
;     ...
;       const float prow = (float)((pq - NMETA) >> 6), pcol = (float)((pq - NMETA) & 63);
;       A_QROPE(0, 2, 0, prow); A_QROPE(1, 3, 1, prow);
;       A_QROPE(4, 6, 0, pcol); A_QROPE(5, 7, 1, pcol);
.LBB0_1216:
	s_ashr_i32 s18, s28, 4
	s_lshr_b32 s19, s18, 29
	s_add_i32 s19, s18, s19
	s_and_b32 s19, s19, -8
	s_sub_i32 s24, s18, s19
	s_ashr_i32 s18, s28, 31
	s_lshr_b32 s18, s18, 25
	s_add_i32 s18, s28, s18
	s_ashr_i32 s41, s18, 7
	s_lshl_b32 s18, s28, 8
	s_and_b32 s25, s18, 0xf00
	s_mul_i32 s18, s41, 0x1010
	s_ashr_i32 s19, s18, 31
	s_lshl_b64 s[20:21], s[18:19], 9
	s_bfe_i32 s19, s24, 0x80000
	s_bfe_u32 s19, s19, 0x2000d
	s_add_i32 s19, s24, s19
	s_sext_i32_i8 s19, s19
	s_lshl_b32 s19, s19, 5
	v_add_u32_e32 v2, s25, v202
	s_and_b32 s22, s19, 0xffffff80
	s_lshl_b32 s19, s41, 8
	v_add_u32_e32 v0, s18, v2
	s_add_i32 s42, s22, s19
	v_mad_i64_i32 v[0:1], s[18:19], v0, s35, v[168:169]
	s_lshl_b32 s18, s24, 7
	s_ashr_i32 s19, s18, 31
	v_lshl_add_u64 v[0:1], s[18:19], 1, v[0:1]
	v_mov_b32_e32 v3, v200
	v_lshl_add_u64 v[0:1], v[0:1], 0, v[170:171]
	global_load_dwordx4 v[68:71], v[0:1], off
	global_load_dwordx4 v[76:79], v[0:1], off offset:32
	global_load_dwordx4 v[64:67], v[0:1], off offset:64
	global_load_dwordx4 v[72:75], v[0:1], off offset:96
	global_load_dwordx4 v[84:87], v[0:1], off offset:128
	global_load_dwordx4 v[92:95], v[0:1], off offset:160
	global_load_dwordx4 v[80:83], v[0:1], off offset:192
	global_load_dwordx4 v[88:91], v[0:1], off offset:224
	v_lshlrev_b32_e32 v17, 3, v3
	v_cvt_f32_i32_e32 v1, v17
	v_add_u32_e32 v173, -16, v2
	v_ashrrev_i32_e32 v0, 6, v173
	v_cvt_f32_i32_e32 v18, v0
	v_mul_f32_e32 v0, 0xbed49a78, v1
	v_cmp_gt_f32_e32 vcc, s36, v0
	global_load_dwordx4 v[28:31], v[166:167], off
	global_load_dwordx4 v[24:27], v[166:167], off offset:16
	v_cndmask_b32_e32 v0, 0, v208, vcc
	v_fmac_f32_e32 v0, 0xbed49a78, v1
	v_exp_f32_e32 v0, v0
	v_cndmask_b32_e32 v1, 0, v209, vcc
	global_load_dwordx4 v[36:39], v[166:167], off offset:128
	global_load_dwordx4 v[32:35], v[166:167], off offset:144
	v_and_b32_e32 v16, 63, v173
	v_ldexp_f32 v19, v0, v1
	v_or_b32_e32 v1, 1, v17
	v_cvt_f32_i32_e32 v1, v1
	v_mul_f32_e32 v0, v19, v18
	v_mul_f32_e32 v2, 0.15915494, v0
	v_floor_f32_e32 v2, v2
	v_fma_f32 v0, v0, 0.15915494, -v2
	v_mul_f32_e32 v2, 0xbed49a78, v1
	v_cmp_gt_f32_e32 vcc, s36, v2
	v_sin_f32_e32 v96, v0
	v_cos_f32_e32 v98, v0
	v_cndmask_b32_e32 v2, 0, v208, vcc
	v_fmac_f32_e32 v2, 0xbed49a78, v1
	v_exp_f32_e32 v1, v2
	v_cndmask_b32_e32 v0, 0, v209, vcc
	v_cvt_f32_ubyte0_e32 v155, v16
	v_mul_f32_e32 v16, v19, v155
	v_ldexp_f32 v20, v1, v0
	v_or_b32_e32 v1, 2, v17
	v_cvt_f32_i32_e32 v1, v1
	v_mul_f32_e32 v0, v20, v18
	v_mul_f32_e32 v2, 0.15915494, v0
	v_floor_f32_e32 v2, v2
	v_fma_f32 v0, v0, 0.15915494, -v2
	v_mul_f32_e32 v2, 0xbed49a78, v1
	v_cmp_gt_f32_e32 vcc, s36, v2
	v_sin_f32_e32 v97, v0
	v_cos_f32_e32 v99, v0
	v_cndmask_b32_e32 v2, 0, v208, vcc
	v_fmac_f32_e32 v2, 0xbed49a78, v1
	v_exp_f32_e32 v1, v2
	v_cndmask_b32_e32 v0, 0, v209, vcc
	s_ashr_i32 s23, s22, 31
	s_add_u32 s24, s29, s20
	v_ldexp_f32 v21, v1, v0
	v_or_b32_e32 v1, 3, v17
	v_cvt_f32_i32_e32 v1, v1
	v_mul_f32_e32 v0, v21, v18
	v_mul_f32_e32 v2, 0.15915494, v0
	v_floor_f32_e32 v2, v2
	v_fma_f32 v0, v0, 0.15915494, -v2
	v_mul_f32_e32 v2, 0xbed49a78, v1
	v_cmp_gt_f32_e32 vcc, s36, v2
	v_sin_f32_e32 v100, v0
	v_cos_f32_e32 v102, v0
	v_cndmask_b32_e32 v2, 0, v208, vcc
	v_fmac_f32_e32 v2, 0xbed49a78, v1
	v_exp_f32_e32 v1, v2
	v_cndmask_b32_e32 v0, 0, v209, vcc
	s_addc_u32 s25, s30, s21
	s_lshl_b64 s[22:23], s[22:23], 1
	v_ldexp_f32 v22, v1, v0
	v_or_b32_e32 v1, 4, v17
	v_cvt_f32_i32_e32 v1, v1
	v_mul_f32_e32 v0, v22, v18
	v_mul_f32_e32 v2, 0.15915494, v0
	v_floor_f32_e32 v2, v2
	v_fma_f32 v0, v0, 0.15915494, -v2
	v_mul_f32_e32 v2, 0xbed49a78, v1
	v_cmp_gt_f32_e32 vcc, s36, v2
	v_sin_f32_e32 v101, v0
	v_cos_f32_e32 v103, v0
	v_cndmask_b32_e32 v2, 0, v208, vcc
	v_fmac_f32_e32 v2, 0xbed49a78, v1
	v_exp_f32_e32 v1, v2
	v_cndmask_b32_e32 v0, 0, v209, vcc
	s_waitcnt vmcnt(11)
	v_and_b32_e32 v223, 0xffff0000, v68
	v_lshlrev_b32_e32 v222, 16, v68
	v_ldexp_f32 v23, v1, v0
	v_or_b32_e32 v1, 5, v17
	v_cvt_f32_i32_e32 v1, v1
	v_mul_f32_e32 v0, v23, v18
	v_mul_f32_e32 v2, 0.15915494, v0
	v_floor_f32_e32 v2, v2
	v_fma_f32 v0, v0, 0.15915494, -v2
	v_mul_f32_e32 v2, 0xbed49a78, v1
	v_cmp_gt_f32_e32 vcc, s36, v2
	v_sin_f32_e32 v140, v0
	v_cos_f32_e32 v142, v0
	v_cndmask_b32_e32 v2, 0, v208, vcc
	v_fmac_f32_e32 v2, 0xbed49a78, v1
	v_exp_f32_e32 v1, v2
	v_cndmask_b32_e32 v0, 0, v209, vcc
	v_mul_f32_e32 v68, v223, v223
	s_waitcnt vmcnt(6)
	v_lshlrev_b32_e32 v158, 16, v95
	v_ldexp_f32 v40, v1, v0
	v_or_b32_e32 v1, 6, v17
	v_cvt_f32_i32_e32 v1, v1
	v_mul_f32_e32 v0, v40, v18
	v_mul_f32_e32 v2, 0.15915494, v0
	v_floor_f32_e32 v2, v2
	v_fma_f32 v0, v0, 0.15915494, -v2
	v_mul_f32_e32 v2, 0xbed49a78, v1
	v_cmp_gt_f32_e32 vcc, s36, v2
	v_sin_f32_e32 v141, v0
	v_cos_f32_e32 v143, v0
	v_cndmask_b32_e32 v2, 0, v208, vcc
	v_fmac_f32_e32 v2, 0xbed49a78, v1
	v_exp_f32_e32 v1, v2
	v_cndmask_b32_e32 v0, 0, v209, vcc
	v_and_b32_e32 v159, 0xffff0000, v95
	s_waitcnt vmcnt(4)
; DI void rope_sc(float pos, int j, float& sn, float& cs) {
;   const float fr = exp2f(-(float)j * (LOG2_THETA / 32.f));
;   float tr = pos * fr * INV_2PI;
;   tr -= floorf(tr);
;   sn = __builtin_amdgcn_sinf(tr);
;   cs = __builtin_amdgcn_cosf(tr);
; }
; template <int NHQ, int NHKV>
; DI void attn_phase_l1(const u16* __restrict__ Q, const u16* __restrict__ K, const u16* __restrict__ Vt, u16* __restrict__ O, const float* __restrict__ qg, char* smem, const int wv) {
;     ...
; #pragma unroll
;       for (int i = 0; i < NS; ++i) {
;         qf[i] = *(const bf16x8*)(qrow + 16 * i);
;         float t8[8]; unpack8(__builtin_bit_cast(u32x4, qf[i]), t8);
; #pragma unroll
;         for (int e = 0; e < 8; ++e) ssq += t8[e] * t8[e];
;       }
;       ssq = xhalf_sum(ssq);
;       const float rn = rsqrtf(ssq * (1.f / DQK) + EPS) * (0.08838834764831845f * 1.4426950408889634f);
;     ...
;       const float prow = (float)((pq - NMETA) >> 6), pcol = (float)((pq - NMETA) & 63);
;       A_QROPE(0, 2, 0, prow); A_QROPE(1, 3, 1, prow);
;       A_QROPE(4, 6, 0, pcol); A_QROPE(5, 7, 1, pcol);
	v_lshlrev_b32_e32 v156, 16, v91
	v_ldexp_f32 v41, v1, v0
	v_or_b32_e32 v1, 7, v17
	v_cvt_f32_i32_e32 v1, v1
	v_mul_f32_e32 v0, v41, v18
	v_mul_f32_e32 v2, 0.15915494, v0
	v_floor_f32_e32 v2, v2
	v_fma_f32 v0, v0, 0.15915494, -v2
	v_mul_f32_e32 v2, 0xbed49a78, v1
	v_cmp_gt_f32_e32 vcc, s36, v2
	v_sin_f32_e32 v180, v0
	v_cos_f32_e32 v182, v0
	v_cndmask_b32_e32 v2, 0, v208, vcc
	v_fmac_f32_e32 v2, 0xbed49a78, v1
	v_exp_f32_e32 v1, v2
	v_cndmask_b32_e32 v0, 0, v209, vcc
	v_and_b32_e32 v157, 0xffff0000, v91
	v_lshlrev_b32_e32 v174, 16, v94
	v_ldexp_f32 v42, v1, v0
	v_mul_f32_e32 v0, v42, v18
	v_mul_f32_e32 v1, 0.15915494, v0
	v_floor_f32_e32 v1, v1
	v_fma_f32 v0, v0, 0.15915494, -v1
	v_add_u32_e32 v1, 16, v17
	v_cvt_f32_i32_e32 v4, v1
	v_and_b32_e32 v175, 0xffff0000, v94
	v_lshlrev_b32_e32 v94, 16, v90
	v_and_b32_e32 v95, 0xffff0000, v90
	v_mul_f32_e32 v5, 0xbed49a78, v4
	v_cmp_gt_f32_e32 vcc, s36, v5
	v_lshlrev_b32_e32 v176, 16, v93
	v_and_b32_e32 v177, 0xffff0000, v93
	v_cndmask_b32_e32 v5, 0, v208, vcc
	v_fmac_f32_e32 v5, 0xbed49a78, v4
	v_exp_f32_e32 v43, v5
	v_cndmask_b32_e32 v44, 0, v209, vcc
	v_lshlrev_b32_e32 v90, 16, v89
	v_and_b32_e32 v91, 0xffff0000, v89
	v_ldexp_f32 v124, v43, v44
	v_add_u32_e32 v44, 17, v17
	v_cvt_f32_i32_e32 v44, v44
	v_mul_f32_e32 v43, v124, v18
	v_mul_f32_e32 v45, 0.15915494, v43
	v_floor_f32_e32 v45, v45
	v_fma_f32 v43, v43, 0.15915494, -v45
	v_mul_f32_e32 v45, 0xbed49a78, v44
	v_cmp_gt_f32_e32 vcc, s36, v45
	v_sin_f32_e32 v104, v43
	v_cos_f32_e32 v106, v43
	v_cndmask_b32_e32 v45, 0, v208, vcc
	v_fmac_f32_e32 v45, 0xbed49a78, v44
	v_exp_f32_e32 v44, v45
	v_cndmask_b32_e32 v43, 0, v209, vcc
	v_lshlrev_b32_e32 v178, 16, v92
	v_and_b32_e32 v179, 0xffff0000, v92
	v_ldexp_f32 v125, v44, v43
	v_add_u32_e32 v44, 18, v17
	v_cvt_f32_i32_e32 v44, v44
	v_mul_f32_e32 v43, v125, v18
	v_mul_f32_e32 v45, 0.15915494, v43
	v_floor_f32_e32 v45, v45
	v_fma_f32 v43, v43, 0.15915494, -v45
	v_mul_f32_e32 v45, 0xbed49a78, v44
	v_cmp_gt_f32_e32 vcc, s36, v45
	v_sin_f32_e32 v105, v43
	v_cos_f32_e32 v107, v43
	v_cndmask_b32_e32 v45, 0, v208, vcc
	v_fmac_f32_e32 v45, 0xbed49a78, v44
	v_exp_f32_e32 v44, v45
	v_cndmask_b32_e32 v43, 0, v209, vcc
	v_lshlrev_b32_e32 v92, 16, v88
	v_and_b32_e32 v93, 0xffff0000, v88
	v_ldexp_f32 v144, v44, v43
	v_add_u32_e32 v44, 19, v17
	v_cvt_f32_i32_e32 v44, v44
	v_mul_f32_e32 v43, v144, v18
	v_mul_f32_e32 v45, 0.15915494, v43
	v_floor_f32_e32 v45, v45
	v_fma_f32 v43, v43, 0.15915494, -v45
	v_mul_f32_e32 v45, 0xbed49a78, v44
	v_cmp_gt_f32_e32 vcc, s36, v45
	v_sin_f32_e32 v108, v43
	v_cos_f32_e32 v110, v43
	v_cndmask_b32_e32 v45, 0, v208, vcc
	v_fmac_f32_e32 v45, 0xbed49a78, v44
	v_exp_f32_e32 v44, v45
	v_cndmask_b32_e32 v43, 0, v209, vcc
	v_lshlrev_b32_e32 v184, 16, v87
	v_and_b32_e32 v185, 0xffff0000, v87
	v_ldexp_f32 v145, v44, v43
	v_add_u32_e32 v44, 20, v17
	v_cvt_f32_i32_e32 v44, v44
	v_mul_f32_e32 v43, v145, v18
	v_mul_f32_e32 v45, 0.15915494, v43
	v_floor_f32_e32 v45, v45
	v_fma_f32 v43, v43, 0.15915494, -v45
	v_mul_f32_e32 v45, 0xbed49a78, v44
	v_cmp_gt_f32_e32 vcc, s36, v45
	v_sin_f32_e32 v109, v43
	v_cos_f32_e32 v111, v43
	v_cndmask_b32_e32 v45, 0, v208, vcc
	v_fmac_f32_e32 v45, 0xbed49a78, v44
	v_exp_f32_e32 v44, v45
	v_cndmask_b32_e32 v43, 0, v209, vcc
	v_lshlrev_b32_e32 v88, 16, v83
	v_and_b32_e32 v89, 0xffff0000, v83
	v_ldexp_f32 v148, v44, v43
	v_add_u32_e32 v44, 21, v17
	v_lshlrev_b32_e32 v186, 16, v86
	v_and_b32_e32 v187, 0xffff0000, v86
	v_lshlrev_b32_e32 v86, 16, v82
	v_and_b32_e32 v87, 0xffff0000, v82
	v_lshlrev_b32_e32 v188, 16, v85
	v_and_b32_e32 v189, 0xffff0000, v85
	v_lshlrev_b32_e32 v82, 16, v81
	v_and_b32_e32 v83, 0xffff0000, v81
	v_lshlrev_b32_e32 v190, 16, v84
	v_and_b32_e32 v191, 0xffff0000, v84
	v_lshlrev_b32_e32 v84, 16, v80
	v_and_b32_e32 v85, 0xffff0000, v80
	v_lshlrev_b32_e32 v192, 16, v79
	v_and_b32_e32 v193, 0xffff0000, v79
	v_lshlrev_b32_e32 v80, 16, v75
	v_and_b32_e32 v81, 0xffff0000, v75
	v_lshlrev_b32_e32 v194, 16, v78
	v_and_b32_e32 v195, 0xffff0000, v78
	v_lshlrev_b32_e32 v78, 16, v74
	v_and_b32_e32 v79, 0xffff0000, v74
	v_lshlrev_b32_e32 v196, 16, v77
	v_and_b32_e32 v197, 0xffff0000, v77
	v_lshlrev_b32_e32 v74, 16, v73
	v_and_b32_e32 v75, 0xffff0000, v73
	v_lshlrev_b32_e32 v198, 16, v76
	v_and_b32_e32 v199, 0xffff0000, v76
	v_lshlrev_b32_e32 v76, 16, v72
	v_and_b32_e32 v77, 0xffff0000, v72
	v_lshlrev_b32_e32 v72, 16, v71
	v_and_b32_e32 v73, 0xffff0000, v71
	v_lshlrev_b32_e32 v214, 16, v67
	v_and_b32_e32 v215, 0xffff0000, v67
	v_lshlrev_b32_e32 v216, 16, v70
	v_and_b32_e32 v217, 0xffff0000, v70
	v_lshlrev_b32_e32 v70, 16, v66
	v_and_b32_e32 v71, 0xffff0000, v66
	v_lshlrev_b32_e32 v66, 16, v69
	v_and_b32_e32 v67, 0xffff0000, v69
	v_pk_fma_f32 v[68:69], v[222:223], v[222:223], v[68:69] op_sel_hi:[1,1,0]
	v_cvt_f32_i32_e32 v44, v44
	v_lshlrev_b32_e32 v220, 16, v65
	v_and_b32_e32 v221, 0xffff0000, v65
	v_lshlrev_b32_e32 v224, 16, v64
	v_and_b32_e32 v225, 0xffff0000, v64
	v_pk_fma_f32 v[64:65], v[66:67], v[66:67], v[68:69]
	v_mul_f32_e32 v68, v67, v67
	v_mul_f32_e32 v43, v148, v18
	v_pk_add_f32 v[64:65], v[68:69], v[64:65] op_sel_hi:[0,1]
	v_mul_f32_e32 v45, 0.15915494, v43
	v_pk_fma_f32 v[64:65], v[216:217], v[216:217], v[64:65]
	v_mul_f32_e32 v68, v217, v217
	v_floor_f32_e32 v45, v45
	v_pk_add_f32 v[64:65], v[68:69], v[64:65] op_sel_hi:[0,1]
	v_fma_f32 v43, v43, 0.15915494, -v45
	v_mul_f32_e32 v45, 0xbed49a78, v44
	v_pk_fma_f32 v[64:65], v[72:73], v[72:73], v[64:65]
	v_mul_f32_e32 v68, v73, v73
	v_cmp_gt_f32_e32 vcc, s36, v45
	v_pk_add_f32 v[64:65], v[68:69], v[64:65] op_sel_hi:[0,1]
	v_pk_fma_f32 v[64:65], v[198:199], v[198:199], v[64:65]
	v_cndmask_b32_e32 v45, 0, v208, vcc
; DI void rope_sc(float pos, int j, float& sn, float& cs) {
;   const float fr = exp2f(-(float)j * (LOG2_THETA / 32.f));
;   float tr = pos * fr * INV_2PI;
;   tr -= floorf(tr);
;   sn = __builtin_amdgcn_sinf(tr);
;   cs = __builtin_amdgcn_cosf(tr);
; }
; template <int NHQ, int NHKV>
; DI void attn_phase_l1(const u16* __restrict__ Q, const u16* __restrict__ K, const u16* __restrict__ Vt, u16* __restrict__ O, const float* __restrict__ qg, char* smem, const int wv) {
;     ...
; #pragma unroll
;       for (int i = 0; i < NS; ++i) {
;         qf[i] = *(const bf16x8*)(qrow + 16 * i);
;         float t8[8]; unpack8(__builtin_bit_cast(u32x4, qf[i]), t8);
; #pragma unroll
;         for (int e = 0; e < 8; ++e) ssq += t8[e] * t8[e];
;       }
;       ssq = xhalf_sum(ssq);
;       const float rn = rsqrtf(ssq * (1.f / DQK) + EPS) * (0.08838834764831845f * 1.4426950408889634f);
;     ...
;       const float prow = (float)((pq - NMETA) >> 6), pcol = (float)((pq - NMETA) & 63);
;       A_QROPE(0, 2, 0, prow); A_QROPE(1, 3, 1, prow);
;       A_QROPE(4, 6, 0, pcol); A_QROPE(5, 7, 1, pcol);
	v_mul_f32_e32 v68, v199, v199
	v_fmac_f32_e32 v45, 0xbed49a78, v44
	v_pk_add_f32 v[64:65], v[68:69], v[64:65] op_sel_hi:[0,1]
	v_exp_f32_e32 v44, v45
	v_pk_fma_f32 v[64:65], v[196:197], v[196:197], v[64:65]
	v_mul_f32_e32 v68, v197, v197
	v_pk_add_f32 v[64:65], v[68:69], v[64:65] op_sel_hi:[0,1]
	v_pk_fma_f32 v[64:65], v[194:195], v[194:195], v[64:65]
	v_mul_f32_e32 v68, v195, v195
	v_sin_f32_e32 v112, v43
	v_cos_f32_e32 v114, v43
	v_cndmask_b32_e32 v43, 0, v209, vcc
	v_pk_add_f32 v[64:65], v[68:69], v[64:65] op_sel_hi:[0,1]
	v_ldexp_f32 v149, v44, v43
	v_add_u32_e32 v44, 22, v17
	v_pk_fma_f32 v[64:65], v[192:193], v[192:193], v[64:65]
	v_mul_f32_e32 v68, v193, v193
	v_cvt_f32_i32_e32 v44, v44
	v_pk_add_f32 v[64:65], v[68:69], v[64:65] op_sel_hi:[0,1]
	v_mul_f32_e32 v43, v149, v18
	v_pk_fma_f32 v[64:65], v[224:225], v[224:225], v[64:65]
	v_mul_f32_e32 v68, v225, v225
	v_mul_f32_e32 v45, 0.15915494, v43
	v_pk_add_f32 v[64:65], v[68:69], v[64:65] op_sel_hi:[0,1]
	v_floor_f32_e32 v45, v45
	v_pk_fma_f32 v[64:65], v[220:221], v[220:221], v[64:65]
	v_mul_f32_e32 v68, v221, v221
	v_fma_f32 v43, v43, 0.15915494, -v45
	v_mul_f32_e32 v45, 0xbed49a78, v44
	v_pk_add_f32 v[64:65], v[68:69], v[64:65] op_sel_hi:[0,1]
	v_cmp_gt_f32_e32 vcc, s36, v45
	v_pk_fma_f32 v[64:65], v[70:71], v[70:71], v[64:65]
	v_mul_f32_e32 v68, v71, v71
	v_cndmask_b32_e32 v45, 0, v208, vcc
	v_pk_add_f32 v[64:65], v[68:69], v[64:65] op_sel_hi:[0,1]
	v_fmac_f32_e32 v45, 0xbed49a78, v44
	v_pk_fma_f32 v[64:65], v[214:215], v[214:215], v[64:65]
	v_mul_f32_e32 v68, v215, v215
	v_exp_f32_e32 v44, v45
	v_pk_add_f32 v[64:65], v[68:69], v[64:65] op_sel_hi:[0,1]
	v_pk_fma_f32 v[64:65], v[76:77], v[76:77], v[64:65]
	v_mul_f32_e32 v68, v77, v77
	v_pk_add_f32 v[64:65], v[68:69], v[64:65] op_sel_hi:[0,1]
	v_sin_f32_e32 v113, v43
	v_cos_f32_e32 v115, v43
	v_cndmask_b32_e32 v43, 0, v209, vcc
	v_add_u32_e32 v17, 23, v17
	v_pk_fma_f32 v[64:65], v[74:75], v[74:75], v[64:65]
	v_mul_f32_e32 v68, v75, v75
	v_ldexp_f32 v152, v44, v43
	v_cvt_f32_i32_e32 v17, v17
	v_pk_add_f32 v[64:65], v[68:69], v[64:65] op_sel_hi:[0,1]
	v_mul_f32_e32 v43, v152, v18
	v_pk_fma_f32 v[64:65], v[78:79], v[78:79], v[64:65]
	v_mul_f32_e32 v68, v79, v79
	v_mul_f32_e32 v44, 0.15915494, v43
	v_pk_add_f32 v[64:65], v[68:69], v[64:65] op_sel_hi:[0,1]
	v_floor_f32_e32 v44, v44
	v_pk_fma_f32 v[64:65], v[80:81], v[80:81], v[64:65]
	v_mul_f32_e32 v68, v81, v81
	v_fma_f32 v43, v43, 0.15915494, -v44
	v_mul_f32_e32 v44, 0xbed49a78, v17
	v_pk_add_f32 v[64:65], v[68:69], v[64:65] op_sel_hi:[0,1]
	v_cmp_gt_f32_e32 vcc, s36, v44
	v_pk_fma_f32 v[64:65], v[190:191], v[190:191], v[64:65]
	v_mul_f32_e32 v68, v191, v191
	v_cndmask_b32_e32 v44, 0, v208, vcc
	v_pk_add_f32 v[64:65], v[68:69], v[64:65] op_sel_hi:[0,1]
	v_fmac_f32_e32 v44, 0xbed49a78, v17
	v_pk_fma_f32 v[64:65], v[188:189], v[188:189], v[64:65]
	v_mul_f32_e32 v68, v189, v189
	v_exp_f32_e32 v17, v44
	v_pk_add_f32 v[64:65], v[68:69], v[64:65] op_sel_hi:[0,1]
	v_pk_fma_f32 v[64:65], v[186:187], v[186:187], v[64:65]
	v_mul_f32_e32 v68, v187, v187
	v_pk_add_f32 v[64:65], v[68:69], v[64:65] op_sel_hi:[0,1]
	v_sin_f32_e32 v132, v43
	v_cos_f32_e32 v134, v43
	v_cndmask_b32_e32 v43, 0, v209, vcc
	v_pk_fma_f32 v[64:65], v[184:185], v[184:185], v[64:65]
	v_mul_f32_e32 v68, v185, v185
	v_ldexp_f32 v153, v17, v43
	v_pk_add_f32 v[64:65], v[68:69], v[64:65] op_sel_hi:[0,1]
	v_mul_f32_e32 v17, v153, v18
	v_pk_fma_f32 v[64:65], v[178:179], v[178:179], v[64:65]
	v_mul_f32_e32 v68, v179, v179
	v_mul_f32_e32 v18, 0.15915494, v17
	v_pk_add_f32 v[64:65], v[68:69], v[64:65] op_sel_hi:[0,1]
	v_floor_f32_e32 v18, v18
	v_pk_fma_f32 v[64:65], v[176:177], v[176:177], v[64:65]
	v_mul_f32_e32 v68, v177, v177
	v_fma_f32 v17, v17, 0.15915494, -v18
	v_pk_add_f32 v[64:65], v[68:69], v[64:65] op_sel_hi:[0,1]
	v_sin_f32_e32 v133, v17
	v_cos_f32_e32 v135, v17
	v_mul_f32_e32 v17, 0.15915494, v16
	v_pk_fma_f32 v[64:65], v[174:175], v[174:175], v[64:65]
	v_mul_f32_e32 v68, v175, v175
	v_floor_f32_e32 v17, v17
	v_pk_add_f32 v[64:65], v[68:69], v[64:65] op_sel_hi:[0,1]
	v_fma_f32 v16, v16, 0.15915494, -v17
	v_pk_fma_f32 v[64:65], v[158:159], v[158:159], v[64:65]
	v_mul_f32_e32 v68, v159, v159
	v_sin_f32_e32 v120, v16
	v_cos_f32_e32 v122, v16
	v_mul_f32_e32 v16, v20, v155
	v_pk_add_f32 v[64:65], v[68:69], v[64:65] op_sel_hi:[0,1]
	v_mul_f32_e32 v17, 0.15915494, v16
	v_pk_fma_f32 v[64:65], v[84:85], v[84:85], v[64:65]
	v_mul_f32_e32 v68, v85, v85
	v_floor_f32_e32 v17, v17
	v_pk_add_f32 v[64:65], v[68:69], v[64:65] op_sel_hi:[0,1]
	v_fma_f32 v16, v16, 0.15915494, -v17
	v_pk_fma_f32 v[64:65], v[82:83], v[82:83], v[64:65]
	v_mul_f32_e32 v68, v83, v83
	v_sin_f32_e32 v121, v16
	v_cos_f32_e32 v123, v16
	v_mul_f32_e32 v16, v21, v155
	v_pk_add_f32 v[64:65], v[68:69], v[64:65] op_sel_hi:[0,1]
	v_mul_f32_e32 v17, 0.15915494, v16
	v_pk_fma_f32 v[64:65], v[86:87], v[86:87], v[64:65]
	v_mul_f32_e32 v68, v87, v87
	v_floor_f32_e32 v17, v17
	v_pk_add_f32 v[64:65], v[68:69], v[64:65] op_sel_hi:[0,1]
	v_fma_f32 v16, v16, 0.15915494, -v17
	v_pk_fma_f32 v[64:65], v[88:89], v[88:89], v[64:65]
	v_mul_f32_e32 v68, v89, v89
	v_sin_f32_e32 v128, v16
	v_cos_f32_e32 v130, v16
	v_mul_f32_e32 v16, v22, v155
	v_pk_add_f32 v[64:65], v[68:69], v[64:65] op_sel_hi:[0,1]
	v_mul_f32_e32 v17, 0.15915494, v16
	v_pk_fma_f32 v[64:65], v[92:93], v[92:93], v[64:65]
	v_mul_f32_e32 v68, v93, v93
	v_floor_f32_e32 v17, v17
	v_pk_add_f32 v[64:65], v[68:69], v[64:65] op_sel_hi:[0,1]
	v_fma_f32 v16, v16, 0.15915494, -v17
	v_pk_fma_f32 v[64:65], v[90:91], v[90:91], v[64:65]
	v_mul_f32_e32 v68, v91, v91
	v_sin_f32_e32 v129, v16
	v_cos_f32_e32 v131, v16
	v_mul_f32_e32 v16, v23, v155
; template <int NHQ, int NHKV>
; DI void attn_phase_l1(const u16* __restrict__ Q, const u16* __restrict__ K, const u16* __restrict__ Vt, u16* __restrict__ O, const float* __restrict__ qg, char* smem, const int wv) {
;     ...
;       ssq = xhalf_sum(ssq);
;       const float rn = rsqrtf(ssq * (1.f / DQK) + EPS) * (0.08838834764831845f * 1.4426950408889634f);
;     ...
;       const float prow = (float)((pq - NMETA) >> 6), pcol = (float)((pq - NMETA) & 63);
;       A_QROPE(0, 2, 0, prow); A_QROPE(1, 3, 1, prow);
;       A_QROPE(4, 6, 0, pcol); A_QROPE(5, 7, 1, pcol);
	v_pk_add_f32 v[64:65], v[68:69], v[64:65] op_sel_hi:[0,1]
	v_mul_f32_e32 v17, 0.15915494, v16
	v_pk_fma_f32 v[64:65], v[94:95], v[94:95], v[64:65]
	v_mul_f32_e32 v68, v95, v95
	v_floor_f32_e32 v17, v17
	v_pk_add_f32 v[64:65], v[68:69], v[64:65] op_sel_hi:[0,1]
	v_fma_f32 v16, v16, 0.15915494, -v17
	v_pk_fma_f32 v[64:65], v[156:157], v[156:157], v[64:65]
	v_mul_f32_e32 v68, v157, v157
	v_sin_f32_e32 v136, v16
	v_cos_f32_e32 v138, v16
	v_mul_f32_e32 v16, v40, v155
	v_pk_add_f32 v[64:65], v[68:69], v[64:65] op_sel_hi:[0,1]
	v_mul_f32_e32 v17, 0.15915494, v16
	v_mov_b32_e32 v65, v64
	v_floor_f32_e32 v17, v17
	s_nop 0
	v_permlane32_swap_b32_e32 v64, v65
	v_fma_f32 v16, v16, 0.15915494, -v17
	v_add_f32_e32 v64, v64, v65
	v_sin_f32_e32 v137, v16
	v_cos_f32_e32 v139, v16
	v_mul_f32_e32 v16, v41, v155
	v_fmamk_f32 v64, v64, 0x3c000000, v210
	v_mul_f32_e32 v17, 0.15915494, v16
	v_mul_f32_e32 v65, 0x4b800000, v64
	v_cmp_gt_f32_e32 vcc, s37, v64
	v_floor_f32_e32 v17, v17
	v_fma_f32 v16, v16, 0.15915494, -v17
	v_cndmask_b32_e32 v64, v64, v65, vcc
	v_mul_f32_e32 v153, v153, v155
	v_rsq_f32_e32 v64, v64
	v_sin_f32_e32 v116, v16
	v_cos_f32_e32 v118, v16
	v_mul_f32_e32 v16, v42, v155
	v_mul_f32_e32 v124, v124, v155
	v_mul_f32_e32 v125, v125, v155
	v_mul_f32_e32 v144, v144, v155
	v_mul_f32_e32 v145, v145, v155
	v_mul_f32_e32 v148, v148, v155
	v_mul_f32_e32 v149, v149, v155
	v_mul_f32_e32 v152, v152, v155
	v_mul_f32_e32 v155, 0.15915494, v153
	v_floor_f32_e32 v155, v155
	v_fma_f32 v65, v153, 0.15915494, -v155
	v_sin_f32_e32 v153, v65
	v_cos_f32_e32 v155, v65
	v_mul_f32_e32 v65, 0x45800000, v64
	v_cndmask_b32_e32 v64, v64, v65, vcc
	v_sin_f32_e32 v181, v0
	v_cos_f32_e32 v183, v0
	global_load_dwordx4 v[8:11], v[166:167], off offset:64
	global_load_dwordx4 v[0:3], v[166:167], off offset:80
	v_mul_f32_e32 v64, 0x3e0293ee, v64
	global_load_dwordx4 v[12:15], v[166:167], off offset:192
	global_load_dwordx4 v[4:7], v[166:167], off offset:208
	s_waitcnt vmcnt(7)
	v_pk_mul_f32 v[28:29], v[28:29], v[64:65] op_sel_hi:[1,0]
	v_pk_mul_f32 v[30:31], v[30:31], v[64:65] op_sel_hi:[1,0]
	v_pk_mul_f32 v[28:29], v[28:29], v[222:223]
	s_waitcnt vmcnt(5)
	v_pk_mul_f32 v[36:37], v[36:37], v[64:65] op_sel_hi:[1,0]
	v_pk_mul_f32 v[30:31], v[30:31], v[66:67]
	v_pk_mul_f32 v[36:37], v[36:37], v[224:225]
	v_pk_mul_f32 v[66:67], v[96:97], v[28:29]
	v_pk_mul_f32 v[38:39], v[38:39], v[64:65] op_sel_hi:[1,0]
	v_pk_fma_f32 v[66:67], v[98:99], v[36:37], v[66:67]
	v_pk_mul_f32 v[36:37], v[96:97], v[36:37]
	v_pk_mul_f32 v[24:25], v[24:25], v[64:65] op_sel_hi:[1,0]
	v_pk_mul_f32 v[38:39], v[38:39], v[220:221]
	v_pk_fma_f32 v[28:29], v[98:99], v[28:29], v[36:37] neg_lo:[0,0,1] neg_hi:[0,0,1]
	v_pk_mul_f32 v[36:37], v[100:101], v[30:31]
	v_pk_mul_f32 v[24:25], v[24:25], v[216:217]
	s_waitcnt vmcnt(4)
	v_pk_mul_f32 v[32:33], v[32:33], v[64:65] op_sel_hi:[1,0]
	v_pk_fma_f32 v[36:37], v[102:103], v[38:39], v[36:37]
	v_pk_mul_f32 v[38:39], v[100:101], v[38:39]
	v_pk_mul_f32 v[26:27], v[26:27], v[64:65] op_sel_hi:[1,0]
	v_pk_mul_f32 v[32:33], v[32:33], v[70:71]
	v_pk_fma_f32 v[30:31], v[102:103], v[30:31], v[38:39] neg_lo:[0,0,1] neg_hi:[0,0,1]
	v_pk_mul_f32 v[38:39], v[140:141], v[24:25]
	s_add_u32 s24, s24, s22
	global_load_dwordx4 v[60:63], v[166:167], off offset:256
	global_load_dwordx4 v[56:59], v[166:167], off offset:272
	global_load_dwordx4 v[52:55], v[166:167], off offset:384
	global_load_dwordx4 v[48:51], v[166:167], off offset:400
	v_pk_mul_f32 v[26:27], v[26:27], v[72:73]
	v_pk_mul_f32 v[34:35], v[34:35], v[64:65] op_sel_hi:[1,0]
	v_pk_fma_f32 v[98:99], v[142:143], v[32:33], v[38:39]
	v_pk_mul_f32 v[32:33], v[140:141], v[32:33]
	s_mul_i32 s26, s42, 0x2080
	s_addc_u32 s25, s25, s23
	v_pk_mul_f32 v[34:35], v[34:35], v[214:215]
	v_pk_fma_f32 v[24:25], v[142:143], v[24:25], v[32:33] neg_lo:[0,0,1] neg_hi:[0,0,1]
	v_pk_mul_f32 v[32:33], v[180:181], v[26:27]
	s_mul_hi_i32 s27, s42, 0x2080
	s_add_u32 s26, s31, s26
	v_pk_fma_f32 v[140:141], v[182:183], v[34:35], v[32:33]
	v_pk_mul_f32 v[32:33], v[180:181], v[34:35]
	v_lshl_add_u64 v[180:181], s[24:25], 0, v[160:161]
	s_addc_u32 s27, s34, s27
	v_pk_fma_f32 v[26:27], v[182:183], v[26:27], v[32:33] neg_lo:[0,0,1] neg_hi:[0,0,1]
	v_add_co_u32_e32 v32, vcc, s38, v180
	v_mul_f32_e32 v17, 0.15915494, v16
	s_nop 0
	v_addc_co_u32_e32 v33, vcc, 0, v181, vcc
	v_lshl_add_u64 v[142:143], s[26:27], 0, v[162:163]
	v_floor_f32_e32 v17, v17
	v_add_co_u32_e32 v182, vcc, s39, v142
	v_fma_f32 v16, v16, 0.15915494, -v17
	v_cvt_pk_bf16_f32 v97, v36, v37
	v_lshl_add_u64 v[36:37], v[180:181], 0, s[8:9]
	v_addc_co_u32_e32 v183, vcc, 0, v143, vcc
	v_sin_f32_e32 v117, v16
	v_cos_f32_e32 v119, v16
	global_load_dwordx4 v[44:47], v[166:167], off offset:320
	global_load_dwordx4 v[40:43], v[166:167], off offset:336
	global_load_dwordx4 v[20:23], v[166:167], off offset:448
	global_load_dwordx4 v[16:19], v[166:167], off offset:464
	v_cvt_pk_bf16_f32 v100, v28, v29
	v_cvt_pk_bf16_f32 v101, v30, v31
	v_cvt_pk_bf16_f32 v102, v24, v25
	v_cvt_pk_bf16_f32 v103, v26, v27
	v_cvt_pk_bf16_f32 v96, v66, v67
	s_barrier
; #define B_LOADK(Kb_, tile_) do { const char* kp_ = (const char*)(Kb_) + (size_t)(tile_) * (64 * LDK * 2); const unsigned ko_ = ((tile_) == NT - 1) ? koffL : koff; \
;     _Pragma("unroll") for (int i_ = 0; i_ < NKC; ++i_) rk[i_] = *(const u32x4*)(kp_ + ko_ + i_ * 128); } while (0)
; #define B_LOADV(Vb_, tile_) do { const char* vp_ = (const char*)(Vb_) + (size_t)(tile_) * 128; \
;     rv[0] = *(const u32x4*)(vp_ + voff); rv[1] = *(const u32x4*)(vp_ + voff + 64 * LP * 2); } while (0)
; #define B_WRITEK(bi_) do { char* b_w = kb0 + (bi_) * KBYTES + kwoff; \
;     _Pragma("unroll") for (int i_ = 0; i_ < NKC; ++i_) *(u32x4*)(b_w + i_ * 128) = rk[i_]; } while (0)
; #define B_WRITEV(bi_) do { char* b_w = vb0 + (bi_) * VBYTES + vwoff; \
;     *(u32x4*)(b_w) = rv[0]; *(u32x4*)(b_w + 64 * VSTR) = rv[1]; } while (0)
; template <int NHQ, int NHKV>
; DI void attn_phase_l1(const u16* __restrict__ Q, const u16* __restrict__ K, const u16* __restrict__ Vt, u16* __restrict__ O, const float* __restrict__ qg, char* smem, const int wv) {
;     ...
;       const float prow = (float)((pq - NMETA) >> 6), pcol = (float)((pq - NMETA) & 63);
;       A_QROPE(0, 2, 0, prow); A_QROPE(1, 3, 1, prow);
;       A_QROPE(4, 6, 0, pcol); A_QROPE(5, 7, 1, pcol);
;     ...
;     }
;     float l = 0.f;
; #pragma unroll
;     for (int d = 0; d < 4; ++d)
; #pragma unroll
;       for (int i = 0; i < 16; ++i) o[d][i] = 0.f;
;     __syncthreads();
;     B_LOADK(Kb, 0); B_WRITEK(0); B_LOADK(Kb, 1); B_WRITEK(1); B_LOADV(Vb, 0); B_WRITEV(0);
;     B_LOADK(Kb, 2); B_LOADV(Vb, 1);
;     __syncthreads();
	global_load_dwordx4 v[24:27], v[180:181], off
	global_load_dwordx4 v[28:31], v[180:181], off offset:128
	s_nop 0
	global_load_dwordx4 v[32:35], v[32:33], off
	s_nop 0
	global_load_dwordx4 v[36:39], v[36:37], off offset:128
	v_cvt_pk_bf16_f32 v98, v98, v99
	global_load_dwordx4 v[66:69], v[142:143], off
	global_load_dwordx4 v[70:73], v[182:183], off
	s_waitcnt vmcnt(5)
	ds_write_b128 v203, v[24:27]
	s_waitcnt vmcnt(4)
	ds_write_b128 v203, v[28:31] offset:128
	s_waitcnt vmcnt(3)
	ds_write_b128 v203, v[32:35] offset:17408
	s_waitcnt vmcnt(2)
	ds_write_b128 v203, v[36:39] offset:17536
	v_pk_mul_f32 v[8:9], v[8:9], v[64:65] op_sel_hi:[1,0]
	v_pk_mul_f32 v[12:13], v[12:13], v[64:65] op_sel_hi:[1,0]
	v_pk_mul_f32 v[8:9], v[8:9], v[198:199]
	v_pk_mul_f32 v[14:15], v[14:15], v[64:65] op_sel_hi:[1,0]
	v_pk_mul_f32 v[10:11], v[10:11], v[64:65] op_sel_hi:[1,0]
	v_pk_mul_f32 v[12:13], v[12:13], v[76:77]
	v_pk_mul_f32 v[14:15], v[14:15], v[74:75]
	v_pk_mul_f32 v[74:75], v[104:105], v[8:9]
	v_pk_mul_f32 v[10:11], v[10:11], v[196:197]
	v_pk_fma_f32 v[74:75], v[106:107], v[12:13], v[74:75]
	v_pk_mul_f32 v[12:13], v[104:105], v[12:13]
	v_pk_mul_f32 v[0:1], v[0:1], v[64:65] op_sel_hi:[1,0]
	v_pk_fma_f32 v[8:9], v[106:107], v[8:9], v[12:13] neg_lo:[0,0,1] neg_hi:[0,0,1]
	v_pk_mul_f32 v[12:13], v[108:109], v[10:11]
	v_pk_mul_f32 v[0:1], v[0:1], v[194:195]
	v_pk_mul_f32 v[4:5], v[4:5], v[64:65] op_sel_hi:[1,0]
	v_pk_fma_f32 v[12:13], v[110:111], v[14:15], v[12:13]
	v_pk_mul_f32 v[14:15], v[108:109], v[14:15]
	v_pk_mul_f32 v[2:3], v[2:3], v[64:65] op_sel_hi:[1,0]
	v_pk_mul_f32 v[4:5], v[4:5], v[78:79]
	v_pk_fma_f32 v[10:11], v[110:111], v[10:11], v[14:15] neg_lo:[0,0,1] neg_hi:[0,0,1]
	v_pk_mul_f32 v[14:15], v[112:113], v[0:1]
	v_pk_mul_f32 v[2:3], v[2:3], v[192:193]
	v_pk_mul_f32 v[6:7], v[6:7], v[64:65] op_sel_hi:[1,0]
	v_pk_fma_f32 v[14:15], v[114:115], v[4:5], v[14:15]
	v_pk_mul_f32 v[4:5], v[112:113], v[4:5]
	v_pk_mul_f32 v[6:7], v[6:7], v[80:81]
	v_pk_fma_f32 v[0:1], v[114:115], v[0:1], v[4:5] neg_lo:[0,0,1] neg_hi:[0,0,1]
	v_pk_mul_f32 v[4:5], v[132:133], v[2:3]
	v_cvt_pk_bf16_f32 v108, v8, v9
	v_pk_mul_f32 v[8:9], v[64:65], v[52:53] op_sel_hi:[0,1]
	v_pk_fma_f32 v[4:5], v[134:135], v[6:7], v[4:5]
	v_cvt_pk_bf16_f32 v110, v0, v1
	v_cvt_pk_bf16_f32 v105, v12, v13
	v_pk_mul_f32 v[0:1], v[60:61], v[64:65] op_sel_hi:[1,0]
	v_pk_mul_f32 v[8:9], v[8:9], v[84:85]
	v_pk_mul_f32 v[12:13], v[64:65], v[54:55] op_sel_hi:[0,1]
	v_pk_mul_f32 v[6:7], v[132:133], v[6:7]
	v_cvt_pk_bf16_f32 v109, v10, v11
	v_cvt_pk_bf16_f32 v107, v4, v5
	v_pk_mul_f32 v[0:1], v[0:1], v[190:191]
	v_pk_mul_f32 v[4:5], v[62:63], v[64:65] op_sel_hi:[1,0]
	v_pk_mul_f32 v[10:11], v[64:65], v[48:49] op_sel_hi:[0,1]
	v_pk_mul_f32 v[12:13], v[12:13], v[82:83]
	v_pk_mul_f32 v[48:49], v[120:121], v[8:9]
	v_pk_mul_f32 v[8:9], v[122:123], v[8:9]
	v_pk_fma_f32 v[2:3], v[134:135], v[2:3], v[6:7] neg_lo:[0,0,1] neg_hi:[0,0,1]
	v_pk_mul_f32 v[4:5], v[4:5], v[188:189]
	v_pk_fma_f32 v[48:49], v[122:123], v[0:1], v[48:49] neg_lo:[0,0,1] neg_hi:[0,0,1]
	v_pk_fma_f32 v[8:9], v[120:121], v[0:1], v[8:9]
	v_pk_mul_f32 v[0:1], v[128:129], v[12:13]
	v_cvt_pk_bf16_f32 v111, v2, v3
	v_cvt_pk_bf16_f32 v106, v14, v15
	v_pk_mul_f32 v[2:3], v[64:65], v[56:57] op_sel_hi:[0,1]
	v_pk_mul_f32 v[10:11], v[10:11], v[86:87]
	v_pk_mul_f32 v[14:15], v[64:65], v[50:51] op_sel_hi:[0,1]
	v_pk_fma_f32 v[50:51], v[130:131], v[4:5], v[0:1] neg_lo:[0,0,1] neg_hi:[0,0,1]
	v_pk_mul_f32 v[0:1], v[130:131], v[12:13]
	v_pk_mul_f32 v[2:3], v[2:3], v[186:187]
	v_pk_fma_f32 v[52:53], v[128:129], v[4:5], v[0:1]
	v_pk_mul_f32 v[0:1], v[136:137], v[10:11]
	v_pk_mul_f32 v[6:7], v[64:65], v[58:59] op_sel_hi:[0,1]
	v_pk_mul_f32 v[14:15], v[14:15], v[88:89]
	v_pk_fma_f32 v[4:5], v[138:139], v[2:3], v[0:1] neg_lo:[0,0,1] neg_hi:[0,0,1]
	v_pk_mul_f32 v[0:1], v[138:139], v[10:11]
	v_pk_mul_f32 v[6:7], v[6:7], v[184:185]
	v_pk_fma_f32 v[54:55], v[136:137], v[2:3], v[0:1]
	v_pk_mul_f32 v[0:1], v[116:117], v[14:15]
	v_add_co_u32_e32 v2, vcc, s40, v180
	v_pk_fma_f32 v[10:11], v[118:119], v[6:7], v[0:1] neg_lo:[0,0,1] neg_hi:[0,0,1]
	s_waitcnt vmcnt(1)
	ds_write_b128 v204, v[66:69] offset:34816
	s_waitcnt vmcnt(0)
	ds_write_b128 v204, v[70:73] offset:44032
	v_lshl_add_u64 v[0:1], v[180:181], 0, s[14:15]
	v_addc_co_u32_e32 v3, vcc, 0, v181, vcc
	v_cvt_pk_bf16_f32 v99, v140, v141
	global_load_dwordx4 v[136:139], v[142:143], off offset:128
	v_pk_mul_f32 v[12:13], v[118:119], v[14:15]
	global_load_dwordx4 v[140:143], v[182:183], off offset:128
	global_load_dwordx4 v[128:131], v[2:3], off
	global_load_dwordx4 v[132:135], v[0:1], off offset:128
	s_waitcnt lgkmcnt(0)
	s_barrier
; DI unsigned cvtpk(float lo, float hi) { f32x2 v = {lo, hi}; return __builtin_bit_cast(unsigned, __builtin_convertvector(v, bf16x2_t)); }
; template <int NHQ, int NHKV>
; DI void attn_phase_l1(const u16* __restrict__ Q, const u16* __restrict__ K, const u16* __restrict__ Vt, u16* __restrict__ O, const float* __restrict__ qg, char* smem, const int wv) {
;     ...
;       const float prow = (float)((pq - NMETA) >> 6), pcol = (float)((pq - NMETA) & 63);
;       A_QROPE(0, 2, 0, prow); A_QROPE(1, 3, 1, prow);
;       A_QROPE(4, 6, 0, pcol); A_QROPE(5, 7, 1, pcol);
;     ...
;     {
;       const char* sk = kb0 + r32 * KSTR + hh * 16;
; #pragma unroll
;       for (int i = 0; i < 16; ++i) { s0[i] = 0.f; s1[i] = 0.f; }
; #pragma unroll
;       for (int i = 0; i < NS; ++i) {
;         const bf16x8 k0f = *(const bf16x8*)(sk + i * 32), k1f = *(const bf16x8*)(sk + 32 * KSTR + i * 32);
;         s0 = __builtin_amdgcn_mfma_f32_32x32x16_bf16(k0f, qf[i], s0, 0, 0, 0);
;         s1 = __builtin_amdgcn_mfma_f32_32x32x16_bf16(k1f, qf[i], s1, 0, 0, 0);
;       }
;       unsigned w_[16]; f32x2 ps2 = {0.f, 0.f};
; #pragma unroll
;       for (int i = 0; i < 8; ++i) { f32x2 v; v[0] = __builtin_amdgcn_exp2f(s0[2 * i]); v[1] = __builtin_amdgcn_exp2f(s0[2 * i + 1]); ps2 += v; w_[i] = cvtpk(v[0], v[1]); }
; #pragma unroll
;       for (int i = 0; i < 8; ++i) { f32x2 v; v[0] = __builtin_amdgcn_exp2f(s1[2 * i]); v[1] = __builtin_amdgcn_exp2f(s1[2 * i + 1]); ps2 += v; w_[8 + i] = cvtpk(v[0], v[1]); }
;       l += ps2[0] + ps2[1];
; #pragma unroll
;       for (int q = 0; q < 4; ++q) pb[q] = __builtin_bit_cast(bf16x8, u32x4{w_[4 * q], w_[4 * q + 1], w_[4 * q + 2], w_[4 * q + 3]});
;     }
	ds_read_b128 v[0:3], v205
	ds_read_b128 v[24:27], v205 offset:32
	v_pk_fma_f32 v[32:33], v[116:117], v[6:7], v[12:13]
	v_cvt_pk_bf16_f32 v118, v4, v5
	v_cvt_pk_bf16_f32 v119, v10, v11
	v_cvt_pk_bf16_f32 v112, v8, v9
	s_waitcnt lgkmcnt(1)
	v_mfma_f32_32x32x16_bf16 v[0:15], v[0:3], v[100:103], 0
	v_mul_f32_e64 v28, v64, v44
	v_mul_f32_e64 v29, v64, v45
	v_mul_f32_e64 v34, v28, v178
	v_mul_f32_e64 v35, v29, v179
	v_mul_f32_e64 v28, v64, v40
	v_mul_f32_e64 v29, v64, v41
	v_pk_mul_f32 v[36:37], v[28:29], v[174:175]
	ds_read_b128 v[28:31], v205 offset:64
	v_pk_mul_f32 v[16:17], v[64:65], v[16:17] op_sel_hi:[0,1]
	v_mul_f32_e32 v126, 0.15915494, v124
	s_waitcnt lgkmcnt(1)
	v_mfma_f32_32x32x16_bf16 v[0:15], v[24:27], v[108:111], v[0:15]
	v_mul_f32_e64 v24, v64, v46
	v_mul_f32_e64 v25, v64, v47
	v_mul_f32_e64 v38, v24, v176
	v_mul_f32_e64 v39, v25, v177
	v_mul_f32_e64 v24, v64, v42
	v_mul_f32_e64 v25, v64, v43
	v_pk_mul_f32 v[40:41], v[24:25], v[158:159]
	ds_read_b128 v[24:27], v205 offset:96
	v_mul_f32_e32 v127, 0.15915494, v125
	v_floor_f32_e32 v126, v126
	s_waitcnt lgkmcnt(1)
	v_mfma_f32_32x32x16_bf16 v[0:15], v[28:31], v[96:99], v[0:15]
	v_mul_f32_e64 v28, v16, v94
	v_mul_f32_e64 v29, v17, v95
	v_mul_f32_e64 v16, v64, v22
	v_mul_f32_e64 v17, v64, v23
	v_floor_f32_e32 v127, v127
	v_mul_f32_e32 v146, 0.15915494, v144
	v_mul_f32_e32 v147, 0.15915494, v145
	v_pk_mul_f32 v[30:31], v[16:17], v[90:91]
	v_pk_mul_f32 v[16:17], v[64:65], v[18:19] op_sel_hi:[0,1]
	v_fma_f32 v126, v124, 0.15915494, -v126
	v_fma_f32 v127, v125, 0.15915494, -v127
	v_floor_f32_e32 v146, v146
	v_floor_f32_e32 v147, v147
	v_mul_f32_e32 v150, 0.15915494, v148
	v_mul_f32_e32 v151, 0.15915494, v149
	v_cvt_pk_bf16_f32 v104, v74, v75
	v_pk_mul_f32 v[44:45], v[16:17], v[156:157]
	ds_read_b128 v[16:19], v205 offset:128
	v_sin_f32_e32 v124, v126
	v_sin_f32_e32 v125, v127
	v_fma_f32 v146, v144, 0.15915494, -v146
	v_fma_f32 v147, v145, 0.15915494, -v147
	v_floor_f32_e32 v150, v150
	v_floor_f32_e32 v151, v151
	s_waitcnt lgkmcnt(1)
	v_mfma_f32_32x32x16_bf16 v[0:15], v[24:27], v[104:107], v[0:15]
	v_cos_f32_e32 v126, v126
	v_cos_f32_e32 v127, v127
	v_sin_f32_e32 v144, v146
	v_sin_f32_e32 v145, v147
	v_fma_f32 v150, v148, 0.15915494, -v150
	v_fma_f32 v151, v149, 0.15915494, -v151
	v_cos_f32_e32 v146, v146
	v_cos_f32_e32 v147, v147
	v_sin_f32_e32 v148, v150
	v_sin_f32_e32 v149, v151
	v_pk_mul_f32 v[20:21], v[64:65], v[20:21] op_sel_hi:[0,1]
	v_cos_f32_e32 v150, v150
	v_cos_f32_e32 v151, v151
	v_pk_mul_f32 v[42:43], v[20:21], v[92:93]
	v_mul_f32_e32 v154, 0.15915494, v152
	v_pk_mul_f32 v[20:21], v[124:125], v[42:43]
	v_floor_f32_e32 v154, v154
	v_pk_fma_f32 v[24:25], v[126:127], v[34:35], v[20:21] neg_lo:[0,0,1] neg_hi:[0,0,1]
	v_pk_mul_f32 v[20:21], v[144:145], v[30:31]
	v_cvt_pk_bf16_f32 v116, v48, v49
	v_pk_fma_f32 v[26:27], v[146:147], v[38:39], v[20:21] neg_lo:[0,0,1] neg_hi:[0,0,1]
	v_pk_mul_f32 v[20:21], v[148:149], v[28:29]
	v_cvt_pk_bf16_f32 v117, v50, v51
	v_pk_fma_f32 v[46:47], v[150:151], v[36:37], v[20:21] neg_lo:[0,0,1] neg_hi:[0,0,1]
	ds_read_b128 v[20:23], v205 offset:160
	v_fma_f32 v154, v152, 0.15915494, -v154
	s_waitcnt lgkmcnt(1)
	v_mfma_f32_32x32x16_bf16 v[0:15], v[16:19], v[116:119], v[0:15]
	v_sin_f32_e32 v152, v154
	v_cos_f32_e32 v154, v154
	v_cvt_pk_bf16_f32 v120, v24, v25
	v_cvt_pk_bf16_f32 v121, v26, v27
	v_pk_mul_f32 v[16:17], v[152:153], v[44:45]
	v_cvt_pk_bf16_f32 v122, v46, v47
	v_pk_fma_f32 v[16:17], v[154:155], v[40:41], v[16:17] neg_lo:[0,0,1] neg_hi:[0,0,1]
	v_cvt_pk_bf16_f32 v113, v52, v53
	v_cvt_pk_bf16_f32 v123, v16, v17
	ds_read_b128 v[16:19], v205 offset:192
	v_cvt_pk_bf16_f32 v114, v54, v55
	s_waitcnt lgkmcnt(1)
	v_mfma_f32_32x32x16_bf16 v[0:15], v[20:23], v[120:123], v[0:15]
	v_mul_f32_e64 v20, v126, v42
	v_mul_f32_e64 v21, v127, v43
	v_cvt_pk_bf16_f32 v115, v32, v33
	v_fma_f32 v24, v124, v34, v20
	v_fma_f32 v25, v125, v35, v21
	v_pk_mul_f32 v[20:21], v[146:147], v[30:31]
	v_pk_mul_f32 v[28:29], v[150:151], v[28:29]
	v_pk_fma_f32 v[26:27], v[144:145], v[38:39], v[20:21]
	ds_read_b128 v[20:23], v205 offset:224
	s_waitcnt lgkmcnt(1)
	v_mfma_f32_32x32x16_bf16 v[0:15], v[16:19], v[112:115], v[0:15]
	v_mul_f32_e64 v18, v154, v44
	v_mul_f32_e64 v19, v155, v45
	v_fma_f32 v16, v148, v36, v28
	v_fma_f32 v17, v149, v37, v29
	v_fma_f32 v18, v152, v40, v18
	v_fma_f32 v19, v153, v41, v19
	v_cvt_pk_bf16_f32 v126, v16, v17
	v_cvt_pk_bf16_f32 v127, v18, v19
	ds_read_b128 v[16:19], v205 offset:8704
	ds_read_b128 v[32:35], v205 offset:8736
	v_cvt_pk_bf16_f32 v124, v24, v25
	v_cvt_pk_bf16_f32 v125, v26, v27
	v_mad_i64_i32 v[174:175], s[24:25], s42, v212, v[162:163]
	s_waitcnt lgkmcnt(2)
	v_mfma_f32_32x32x16_bf16 v[0:15], v[20:23], v[124:127], v[0:15]
	s_add_u32 s24, s20, s22
	s_addc_u32 s25, s21, s23
	s_mov_b32 s42, -1
	v_mov_b32_e32 v50, v165
	v_mov_b32_e32 v51, v165
	v_mov_b32_e32 v52, v165
	v_mov_b32_e32 v53, v165
	s_waitcnt lgkmcnt(1)
	v_mfma_f32_32x32x16_bf16 v[16:31], v[16:19], v[100:103], 0
	s_nop 2
	v_exp_f32_e32 v44, v0
	v_exp_f32_e32 v45, v1
	v_exp_f32_e32 v46, v2
	v_exp_f32_e32 v47, v3
	v_exp_f32_e32 v4, v4
	v_exp_f32_e32 v5, v5
	v_exp_f32_e32 v6, v6
	s_waitcnt lgkmcnt(0)
	v_mfma_f32_32x32x16_bf16 v[16:31], v[32:35], v[108:111], v[16:31]
	ds_read_b128 v[32:35], v205 offset:8768
	ds_read_b128 v[36:39], v205 offset:8800
	v_exp_f32_e32 v7, v7
	v_pk_add_f32 v[48:49], v[44:45], 0 op_sel_hi:[1,0]
	v_cvt_pk_bf16_f32 v80, v44, v45
	v_pk_add_f32 v[44:45], v[46:47], v[48:49]
	v_exp_f32_e32 v8, v8
	v_exp_f32_e32 v9, v9
	s_waitcnt lgkmcnt(1)
	v_mfma_f32_32x32x16_bf16 v[16:31], v[32:35], v[96:99], v[16:31]
	ds_read_b128 v[32:35], v205 offset:8832
	ds_read_b128 v[40:43], v205 offset:8864
	v_exp_f32_e32 v10, v10
	v_exp_f32_e32 v11, v11
	v_cvt_pk_bf16_f32 v146, v4, v5
	v_cvt_pk_bf16_f32 v147, v6, v7
	v_cvt_pk_bf16_f32 v145, v46, v47
	v_cvt_pk_bf16_f32 v84, v8, v9
	s_waitcnt lgkmcnt(2)
	v_mfma_f32_32x32x16_bf16 v[16:31], v[36:39], v[104:107], v[16:31]
	ds_read_b128 v[0:3], v205 offset:8896
	ds_read_b128 v[36:39], v205 offset:8928
	s_waitcnt lgkmcnt(0)
	s_barrier
; template <int NHQ, int NHKV>
; DI void attn_phase_l1(const u16* __restrict__ Q, const u16* __restrict__ K, const u16* __restrict__ Vt, u16* __restrict__ O, const float* __restrict__ qg, char* smem, const int wv) {
;     ...
;       unsigned w_[16]; f32x2 ps2 = {0.f, 0.f};
; #pragma unroll
;       for (int i = 0; i < 8; ++i) { f32x2 v; v[0] = __builtin_amdgcn_exp2f(s0[2 * i]); v[1] = __builtin_amdgcn_exp2f(s0[2 * i + 1]); ps2 += v; w_[i] = cvtpk(v[0], v[1]); }
; #pragma unroll
;       for (int i = 0; i < 8; ++i) { f32x2 v; v[0] = __builtin_amdgcn_exp2f(s1[2 * i]); v[1] = __builtin_amdgcn_exp2f(s1[2 * i + 1]); ps2 += v; w_[8 + i] = cvtpk(v[0], v[1]); }
;       l += ps2[0] + ps2[1];
; #pragma unroll
;       for (int q = 0; q < 4; ++q) pb[q] = __builtin_bit_cast(bf16x8, u32x4{w_[4 * q], w_[4 * q + 1], w_[4 * q + 2], w_[4 * q + 3]});
;     }
;     asm volatile("s_waitcnt lgkmcnt(0)" ::: "memory"); __builtin_amdgcn_s_barrier(); asm volatile("" ::: "memory");
;     for (int j = 0; j < NT; ++j) {
;       if (j + 2 < NT) B_WRITEK(j & 1);
;       if (j + 1 < NT) B_WRITEV((j + 1) & 1);
;       __builtin_amdgcn_sched_barrier(0);
;       if (j + 3 < NT) B_LOADK(Kb, j + 3);
;       if (j + 2 < NT) B_LOADV(Vb, j + 2);
;       __builtin_amdgcn_sched_barrier(0);
;       if (j == NT - 1) {
;         const char* svl = vb0 + (j & 1) * VBYTES + r32 * VSTR + hh * 16;
;         bf16x8 vf[4];
; #pragma unroll
;         for (int d = 0; d < 4; ++d) vf[d] = *(const bf16x8*)(svl + d * 32 * VSTR);
; #pragma unroll
;         for (int d = 0; d < 4; ++d) o[d] = __builtin_amdgcn_mfma_f32_32x32x16_bf16(vf[d], pb[0], o[d], 0, 0, 0);
;       } else {
;         constexpr int NQK = 2 * NS, NM = NQK + 16, RING = 8;
;         const char* sk = kb0 + ((j + 1) & 1) * KBYTES + r32 * KSTR + hh * 16;
;         const char* sv = vb0 + (j & 1) * VBYTES + r32 * VSTR + hh * 16;
;         bf16x8 ring[RING];
;         unsigned w_[16]; f32x2 ps2 = {0.f, 0.f};
;     ...
; #pragma unroll
;         for (int i = 0; i < 16; ++i) { s0[i] = 0.f; s1[i] = 0.f; }
; #pragma unroll
;         for (int i = 0; i < RING; ++i) B_FRAG(ring[i], i);
; #pragma unroll
;         for (int i = 0; i < NM; ++i) {
;           if (i < NQK) {
;             if (i & 1) s1 = __builtin_amdgcn_mfma_f32_32x32x16_bf16(ring[i % RING], qf[i >> 1], s1, 0, 0, 0);
	v_cvt_pk_bf16_f32 v149, v10, v11
	v_mov_b32_e32 v48, v165
	v_mov_b32_e32 v49, v165
	s_waitcnt lgkmcnt(3)
	v_mfma_f32_32x32x16_bf16 v[16:31], v[32:35], v[116:119], v[16:31]
	v_add_f32_e64 v32, v4, v44
	v_add_f32_e64 v33, v5, v45
	v_mov_b32_e32 v54, v165
	v_add_f32_e64 v4, v6, v32
	v_add_f32_e64 v5, v7, v33
	v_exp_f32_e32 v6, v12
	v_exp_f32_e32 v7, v13
	v_pk_add_f32 v[4:5], v[8:9], v[4:5]
	v_mov_b32_e32 v55, v165
	s_waitcnt lgkmcnt(2)
	v_mfma_f32_32x32x16_bf16 v[16:31], v[40:43], v[120:123], v[16:31]
	v_add_f32_e64 v4, v10, v4
	v_add_f32_e64 v5, v11, v5
	v_cvt_pk_bf16_f32 v150, v6, v7
	v_mov_b32_e32 v56, v165
	v_mov_b32_e32 v57, v165
	v_mov_b32_e32 v58, v165
	v_mov_b32_e32 v59, v165
	v_mov_b32_e32 v60, v165
	s_waitcnt lgkmcnt(1)
	v_mfma_f32_32x32x16_bf16 v[16:31], v[0:3], v[112:115], v[16:31]
	v_exp_f32_e32 v0, v14
	v_exp_f32_e32 v1, v15
	v_pk_add_f32 v[2:3], v[6:7], v[4:5]
	v_mov_b32_e32 v61, v165
	v_mov_b32_e32 v62, v165
	v_pk_add_f32 v[2:3], v[0:1], v[2:3]
	v_cvt_pk_bf16_f32 v151, v0, v1
	s_waitcnt lgkmcnt(0)
	v_mfma_f32_32x32x16_bf16 v[16:31], v[36:39], v[124:127], v[16:31]
	v_mov_b32_e32 v63, v165
	v_mov_b32_e32 v32, v165
	v_mov_b32_e32 v33, v165
	v_mov_b32_e32 v34, v165
	v_mov_b32_e32 v35, v165
	v_mov_b32_e32 v36, v165
	v_mov_b32_e32 v37, v165
	s_nop 4
	v_exp_f32_e32 v4, v16
	v_exp_f32_e32 v5, v17
	v_exp_f32_e32 v6, v18
	v_exp_f32_e32 v7, v19
	v_mov_b32_e32 v38, v165
	v_pk_add_f32 v[0:1], v[2:3], v[4:5]
	v_exp_f32_e32 v2, v20
	v_exp_f32_e32 v3, v21
	v_cvt_pk_bf16_f32 v88, v4, v5
	v_pk_add_f32 v[0:1], v[6:7], v[0:1]
	v_exp_f32_e32 v4, v22
	v_exp_f32_e32 v5, v23
	v_pk_add_f32 v[0:1], v[2:3], v[0:1]
	v_cvt_pk_bf16_f32 v154, v2, v3
	v_exp_f32_e32 v2, v24
	v_exp_f32_e32 v3, v25
	v_cvt_pk_bf16_f32 v153, v6, v7
	v_pk_add_f32 v[0:1], v[4:5], v[0:1]
	v_exp_f32_e32 v6, v26
	v_exp_f32_e32 v7, v27
	v_pk_add_f32 v[0:1], v[2:3], v[0:1]
	v_cvt_pk_bf16_f32 v92, v2, v3
	v_exp_f32_e32 v2, v28
	v_exp_f32_e32 v3, v29
	v_cvt_pk_bf16_f32 v155, v4, v5
	v_exp_f32_e32 v4, v30
	v_exp_f32_e32 v5, v31
	v_pk_add_f32 v[0:1], v[6:7], v[0:1]
	v_cvt_pk_bf16_f32 v157, v6, v7
	v_pk_add_f32 v[0:1], v[2:3], v[0:1]
	v_cvt_pk_bf16_f32 v158, v2, v3
	v_pk_add_f32 v[0:1], v[4:5], v[0:1]
	v_cvt_pk_bf16_f32 v159, v4, v5
	v_add_f32_e32 v0, v0, v1
	v_add_f32_e32 v176, 0, v0
	v_mov_b32_e32 v39, v165
	v_mov_b32_e32 v40, v165
	v_mov_b32_e32 v41, v165
	v_mov_b32_e32 v42, v165
	v_mov_b32_e32 v43, v165
	v_mov_b32_e32 v44, v165
	v_mov_b32_e32 v45, v165
	v_mov_b32_e32 v46, v165
	v_mov_b32_e32 v47, v165
	v_mov_b32_e32 v16, v165
	v_mov_b32_e32 v17, v165
	v_mov_b32_e32 v18, v165
	v_mov_b32_e32 v19, v165
	v_mov_b32_e32 v20, v165
	v_mov_b32_e32 v21, v165
	v_mov_b32_e32 v22, v165
	v_mov_b32_e32 v23, v165
	v_mov_b32_e32 v24, v165
	v_mov_b32_e32 v25, v165
	v_mov_b32_e32 v26, v165
	v_mov_b32_e32 v27, v165
	v_mov_b32_e32 v28, v165
	v_mov_b32_e32 v29, v165
	v_mov_b32_e32 v30, v165
	v_mov_b32_e32 v31, v165
	v_mov_b32_e32 v0, v165
	v_mov_b32_e32 v1, v165
	v_mov_b32_e32 v2, v165
	v_mov_b32_e32 v3, v165
	v_mov_b32_e32 v4, v165
	v_mov_b32_e32 v5, v165
	v_mov_b32_e32 v6, v165
	v_mov_b32_e32 v7, v165
	v_mov_b32_e32 v8, v165
	v_mov_b32_e32 v9, v165
	v_mov_b32_e32 v10, v165
	v_mov_b32_e32 v11, v165
	v_mov_b32_e32 v12, v165
	v_mov_b32_e32 v13, v165
	v_mov_b32_e32 v14, v165
	v_mov_b32_e32 v15, v165
	s_cmp_ge_u32 s3, 4
	s_cbranch_scc1 .Lb_first
	s_branch .La_entry
	.p2align 3
.LBB0_1217:
	s_barrier
.La_entry:
	s_bitcmp1_b32 s42, 0
	s_cselect_b32 s99, 0x4400, 0
	v_add_u32_e32 v164, s99, v205
	ds_read_b128 v[64:67], v164
	ds_read_b128 v[178:181], v164 offset:32
	ds_read_b128 v[182:185], v164 offset:8736
	ds_read_b128 v[186:189], v164 offset:8768
	ds_read_b128 v[190:193], v164 offset:64
	ds_read_b128 v[194:197], v164 offset:96
	ds_read_b128 v[214:217], v164 offset:8800
	s_add_i32 s27, s42, 1
	s_bitcmp1_b32 s27, 0
	s_cselect_b64 s[20:21], -1, 0
	s_and_b64 s[22:23], s[20:21], exec
	s_cselect_b32 s26, 0x4400, 0
	s_bitcmp1_b32 s42, 0
	s_cselect_b64 s[22:23], -1, 0
	s_and_b64 s[44:45], s[22:23], exec
	s_cselect_b32 s43, 0x4800, 0
	v_mov_b32_e32 v156, v92
	v_mov_b32_e32 v152, v88
	v_mov_b32_e32 v148, v84
	v_mov_b32_e32 v144, v80
	s_waitcnt lgkmcnt(6)
	v_mfma_f32_32x32x16_bf16 v[80:95], v[64:67], v[100:103], 0
	ds_read_b128 v[68:71], v164 offset:8704
	ds_read_b128 v[220:223], v164 offset:128
	s_and_b64 s[20:21], s[20:21], exec
	s_cselect_b32 s20, 0x4800, 0
	v_add_u32_e32 v177, s20, v206
	ds_read_b128 v[224:227], v164 offset:8832
	s_waitcnt lgkmcnt(2)
	v_mfma_f32_32x32x16_bf16 v[64:79], v[68:71], v[100:103], 0
	v_mfma_f32_32x32x16_bf16 v[80:95], v[178:181], v[108:111], v[80:95]
	ds_read_b128 v[228:231], v164 offset:160
	ds_read_b128 v[178:181], v164 offset:8864
	s_waitcnt vmcnt(0)
	v_add_u32_e32 v238, s26, v203
	ds_write_b128 v238, v[128:131]
	v_mfma_f32_32x32x16_bf16 v[64:79], v[182:185], v[108:111], v[64:79]
	ds_write_b128 v238, v[132:135] offset:128
	v_mfma_f32_32x32x16_bf16 v[80:95], v[190:193], v[96:99], v[80:95]
	ds_read_b128 v[182:185], v164 offset:192
	ds_read_b128 v[190:193], v164 offset:8896
	v_add_u32_e32 v239, s43, v204
	ds_write_b128 v239, v[136:139] offset:34816
	v_mfma_f32_32x32x16_bf16 v[64:79], v[186:189], v[96:99], v[64:79]
	ds_write_b128 v239, v[140:143] offset:44032
	v_mfma_f32_32x32x16_bf16 v[80:95], v[194:197], v[104:107], v[80:95]
	ds_read_b128 v[186:189], v164 offset:224
	ds_read_b128 v[194:197], v164 offset:8928
	s_cmp_gt_u32 s27, 61
	s_cbranch_scc1 .Lmy_a1_skipk
	s_cmp_eq_u32 s42, 60
	s_cselect_b64 vcc, -1, 0
	s_add_u32 s42, s6, s24
	v_cndmask_b32_e32 v242, v160, v201, vcc
	s_addc_u32 s43, s7, s25
	v_mov_b32_e32 v243, 0
	v_lshl_add_u64 v[240:241], s[42:43], 0, v[242:243]
	v_add_co_u32_e32 v240, vcc, 0x38b18000, v240
	s_nop 1
	v_addc_co_u32_e32 v241, vcc, 0, v241, vcc
	global_load_dwordx4 v[128:131], v[240:241], off
	global_load_dwordx4 v[132:135], v[240:241], off offset:128
; DI unsigned cvtpk(float lo, float hi) { f32x2 v = {lo, hi}; return __builtin_bit_cast(unsigned, __builtin_convertvector(v, bf16x2_t)); }
; template <int NHQ, int NHKV>
; DI void attn_phase_l1(const u16* __restrict__ Q, const u16* __restrict__ K, const u16* __restrict__ Vt, u16* __restrict__ O, const float* __restrict__ qg, char* smem, const int wv) {
;     ...
;         for (int i = 0; i < NM; ++i) {
;           if (i < NQK) {
;             if (i & 1) s1 = __builtin_amdgcn_mfma_f32_32x32x16_bf16(ring[i % RING], qf[i >> 1], s1, 0, 0, 0);
;             else       s0 = __builtin_amdgcn_mfma_f32_32x32x16_bf16(ring[i % RING], qf[i >> 1], s0, 0, 0, 0);
;           } else {
;             o[(i - NQK) & 3] = __builtin_amdgcn_mfma_f32_32x32x16_bf16(ring[i % RING], pb[(i - NQK) >> 2], o[(i - NQK) & 3], 0, 0, 0);
;           }
;           if (i + RING < NM) B_FRAG(ring[i % RING], i + RING);
;           if (i >= NQK + 2) {
;             const int g = i - NQK - 2;
;             f32x2 v;
;             if (g < 8) { v[0] = __builtin_amdgcn_exp2f(s0[2 * g]); v[1] = __builtin_amdgcn_exp2f(s0[2 * g + 1]); }
;             else       { v[0] = __builtin_amdgcn_exp2f(s1[2 * (g - 8)]); v[1] = __builtin_amdgcn_exp2f(s1[2 * (g - 8) + 1]); }
;             ps2 += v; w_[g] = cvtpk(v[0], v[1]);
;           }
;           __builtin_amdgcn_sched_barrier(0);
;         }
; #pragma unroll
;         for (int g = 14; g < 16; ++g) { f32x2 v; v[0] = __builtin_amdgcn_exp2f(s1[2 * (g - 8)]); v[1] = __builtin_amdgcn_exp2f(s1[2 * (g - 8) + 1]); ps2 += v; w_[g] = cvtpk(v[0], v[1]); }
;     ...
;         if (j + 1 == NT - 1) {
;           ps2 = f32x2{0.f, 0.f};
; #pragma unroll
;           for (int g = 0; g < 4; ++g) { ps2[0] += __builtin_amdgcn_exp2f(s0[2 * g]); ps2[1] += __builtin_amdgcn_exp2f(s0[2 * g + 1]); }
; #pragma unroll
;           for (int g = 4; g < 16; ++g) w_[g] = 0u;
;         }
;         if (j + 1 < NT) {
;           l += ps2[0] + ps2[1];
; #pragma unroll
;           for (int q = 0; q < 4; ++q) pb[q] = __builtin_bit_cast(bf16x8, u32x4{w_[4 * q], w_[4 * q + 1], w_[4 * q + 2], w_[4 * q + 3]});
;         }
;       }
;       asm volatile("s_waitcnt lgkmcnt(0)" ::: "memory"); __builtin_amdgcn_s_barrier(); asm volatile("" ::: "memory");
.Lmy_a1_skipk:
	v_mfma_f32_32x32x16_bf16 v[64:79], v[214:217], v[104:107], v[64:79]
	v_lshl_add_u64 v[240:241], s[6:7], 0, v[174:175]
	v_add_co_u32_e32 v244, vcc, 0x29900000, v240
	s_nop 1
	v_addc_co_u32_e32 v245, vcc, 0, v241, vcc
	v_add_co_u32_e32 v240, vcc, 0x29982000, v240
	s_nop 1
	v_addc_co_u32_e32 v241, vcc, 0, v241, vcc
	global_load_dwordx4 v[136:139], v[244:245], off offset:256
	global_load_dwordx4 v[140:143], v[240:241], off offset:256
	s_waitcnt lgkmcnt(11)
	v_mfma_f32_32x32x16_bf16 v[80:95], v[220:223], v[116:119], v[80:95]
	ds_read_b128 v[214:217], v177 offset:34816
	ds_read_b128 v[220:223], v177 offset:39424
	s_waitcnt lgkmcnt(11)
	v_mfma_f32_32x32x16_bf16 v[64:79], v[224:227], v[116:119], v[64:79]
	v_mfma_f32_32x32x16_bf16 v[80:95], v[228:231], v[120:123], v[80:95]
	ds_read_b128 v[224:227], v177 offset:44032
	ds_read_b128 v[228:231], v177 offset:48640
	s_waitcnt lgkmcnt(9)
	v_mfma_f32_32x32x16_bf16 v[64:79], v[178:181], v[120:123], v[64:79]
	v_mfma_f32_32x32x16_bf16 v[80:95], v[182:185], v[112:115], v[80:95]
	ds_read_b128 v[178:181], v177 offset:34848
	ds_read_b128 v[182:185], v177 offset:39456
	s_waitcnt lgkmcnt(7)
	v_mfma_f32_32x32x16_bf16 v[64:79], v[190:193], v[112:115], v[64:79]
	v_mfma_f32_32x32x16_bf16 v[80:95], v[186:189], v[124:127], v[80:95]
	ds_read_b128 v[190:193], v177 offset:44064
	ds_read_b128 v[186:189], v177 offset:48672
	s_waitcnt lgkmcnt(7)
	v_mfma_f32_32x32x16_bf16 v[64:79], v[194:197], v[124:127], v[64:79]
	v_mfma_f32_32x32x16_bf16 v[48:63], v[214:217], v[144:147], v[48:63]
	ds_read_b128 v[194:197], v177 offset:34880
	s_waitcnt lgkmcnt(7)
	v_mfma_f32_32x32x16_bf16 v[32:47], v[220:223], v[144:147], v[32:47]
	ds_read_b128 v[214:217], v177 offset:39488
	s_waitcnt lgkmcnt(7)
	v_mfma_f32_32x32x16_bf16 v[16:31], v[224:227], v[144:147], v[16:31]
	s_nop 0
	v_exp_f32_e32 v80, v80
	v_exp_f32_e32 v81, v81
	ds_read_b128 v[220:223], v177 offset:44096
	v_mov_b32_e32 v198, v80
	v_mov_b32_e32 v199, v81
	v_cvt_pk_bf16_f32 v80, v80, v81
	s_waitcnt lgkmcnt(7)
	v_mfma_f32_32x32x16_bf16 v[0:15], v[228:231], v[144:147], v[0:15]
	v_exp_f32_e32 v82, v82
	v_exp_f32_e32 v83, v83
	ds_read_b128 v[224:227], v177 offset:48704
	v_cvt_pk_bf16_f32 v145, v82, v83
	v_add_f32_e32 v198, v82, v198
	v_add_f32_e32 v199, v83, v199
	s_waitcnt lgkmcnt(7)
	v_mfma_f32_32x32x16_bf16 v[48:63], v[178:181], v[148:151], v[48:63]
	v_exp_f32_e32 v82, v84
	v_exp_f32_e32 v83, v85
	ds_read_b128 v[228:231], v177 offset:34912
	v_add_f32_e32 v84, v82, v198
	v_add_f32_e32 v85, v83, v199
	v_cvt_pk_bf16_f32 v146, v82, v83
	s_waitcnt lgkmcnt(7)
	v_mfma_f32_32x32x16_bf16 v[32:47], v[182:185], v[148:151], v[32:47]
	v_exp_f32_e32 v82, v86
	v_exp_f32_e32 v83, v87
	ds_read_b128 v[178:181], v177 offset:39520
	v_add_f32_e32 v84, v82, v84
	v_add_f32_e32 v85, v83, v85
	v_cvt_pk_bf16_f32 v147, v82, v83
	s_waitcnt lgkmcnt(7)
	v_mfma_f32_32x32x16_bf16 v[16:31], v[190:193], v[148:151], v[16:31]
	v_exp_f32_e32 v82, v88
	v_exp_f32_e32 v83, v89
	ds_read_b128 v[182:185], v177 offset:44128
	v_add_f32_e32 v86, v82, v84
	v_add_f32_e32 v87, v83, v85
	v_cvt_pk_bf16_f32 v84, v82, v83
	s_waitcnt lgkmcnt(7)
	v_mfma_f32_32x32x16_bf16 v[0:15], v[186:189], v[148:151], v[0:15]
	v_exp_f32_e32 v82, v90
	v_exp_f32_e32 v83, v91
	ds_read_b128 v[190:193], v177 offset:48736
	v_cvt_pk_bf16_f32 v149, v82, v83
	v_add_f32_e32 v86, v82, v86
	v_add_f32_e32 v87, v83, v87
	s_waitcnt lgkmcnt(7)
	v_mfma_f32_32x32x16_bf16 v[48:63], v[194:197], v[152:155], v[48:63]
	v_exp_f32_e32 v82, v92
	v_exp_f32_e32 v83, v93
	s_nop 0
	v_cvt_pk_bf16_f32 v150, v82, v83
	v_add_f32_e32 v86, v82, v86
	v_add_f32_e32 v87, v83, v87
	s_waitcnt lgkmcnt(6)
	v_mfma_f32_32x32x16_bf16 v[32:47], v[214:217], v[152:155], v[32:47]
	v_exp_f32_e32 v82, v94
	v_exp_f32_e32 v83, v95
	s_nop 0
	v_cvt_pk_bf16_f32 v151, v82, v83
	v_add_f32_e32 v86, v82, v86
	v_add_f32_e32 v87, v83, v87
	s_waitcnt lgkmcnt(5)
	v_mfma_f32_32x32x16_bf16 v[16:31], v[220:223], v[152:155], v[16:31]
	v_exp_f32_e32 v64, v64
	v_exp_f32_e32 v65, v65
	s_nop 0
	v_cvt_pk_bf16_f32 v88, v64, v65
	v_add_f32_e32 v82, v64, v86
	v_add_f32_e32 v83, v65, v87
	s_waitcnt lgkmcnt(4)
	v_mfma_f32_32x32x16_bf16 v[0:15], v[224:227], v[152:155], v[0:15]
	v_exp_f32_e32 v64, v66
	v_exp_f32_e32 v65, v67
	s_nop 0
	v_cvt_pk_bf16_f32 v153, v64, v65
	v_add_f32_e32 v66, v64, v82
	v_add_f32_e32 v67, v65, v83
	s_waitcnt lgkmcnt(3)
	v_mfma_f32_32x32x16_bf16 v[48:63], v[228:231], v[156:159], v[48:63]
	v_exp_f32_e32 v64, v68
	v_exp_f32_e32 v65, v69
	s_nop 0
	v_cvt_pk_bf16_f32 v154, v64, v65
	v_add_f32_e32 v66, v64, v66
	v_add_f32_e32 v67, v65, v67
	s_waitcnt lgkmcnt(2)
	v_mfma_f32_32x32x16_bf16 v[32:47], v[178:181], v[156:159], v[32:47]
	v_exp_f32_e32 v64, v70
	v_exp_f32_e32 v65, v71
	s_nop 0
	v_cvt_pk_bf16_f32 v155, v64, v65
	v_add_f32_e32 v66, v64, v66
	v_add_f32_e32 v67, v65, v67
	s_waitcnt lgkmcnt(1)
	v_mfma_f32_32x32x16_bf16 v[16:31], v[182:185], v[156:159], v[16:31]
	v_exp_f32_e32 v64, v72
	v_exp_f32_e32 v65, v73
	s_nop 0
	v_cvt_pk_bf16_f32 v92, v64, v65
	v_add_f32_e32 v66, v64, v66
	v_add_f32_e32 v67, v65, v67
	s_waitcnt lgkmcnt(0)
	v_mfma_f32_32x32x16_bf16 v[0:15], v[190:193], v[156:159], v[0:15]
	v_exp_f32_e32 v64, v74
	v_exp_f32_e32 v65, v75
	s_nop 0
	v_cvt_pk_bf16_f32 v157, v64, v65
	v_add_f32_e32 v64, v64, v66
	v_add_f32_e32 v65, v65, v67
	v_exp_f32_e32 v66, v76
	v_exp_f32_e32 v67, v77
	v_exp_f32_e32 v68, v78
	v_exp_f32_e32 v69, v79
	s_waitcnt lgkmcnt(0)
	v_add_f32_e32 v64, v66, v64
	v_add_f32_e32 v65, v67, v65
	v_add_f32_e32 v64, v68, v64
	v_add_f32_e32 v65, v69, v65
	s_add_u32 s24, s24, 0x8000
	v_add_f32_e32 v64, v64, v65
	s_addc_u32 s25, s25, 0
	v_cvt_pk_bf16_f32 v158, v66, v67
	v_cvt_pk_bf16_f32 v159, v68, v69
	v_add_f32_e32 v176, v176, v64
	s_cmp_eq_u32 s27, 62
	v_lshl_add_u64 v[174:175], v[174:175], 0, s[16:17]
	s_cbranch_scc1 .La_exitbar
	s_mov_b32 s42, s27
	s_branch .LBB0_1217
.La_exitbar:
	s_barrier
	s_branch .LBB0_1215
